# neighbourhood attention: 16 bias gathers per tile issued together with one wait and v_cndmask select instead of 16 exec-masked serial LDS round trips
# speedup vs baseline: 1.0029x; 1.0029x over previous
.LBB0_387:
	s_mul_i32 s71, s70, 0xa0
	v_or_b32_e32 v0, s71, v109
	v_mul_hi_u32 v34, v0, s51
	v_lshrrev_b32_e32 v34, 5, v34
	v_mul_i32_i24_e32 v35, 0xffffffd8, v34
	v_add_lshl_u32 v34, v34, v111, 6
	v_add_u32_e32 v0, v0, v112
	v_add3_u32 v34, v0, v35, v34
	v_ashrrev_i32_e32 v35, 31, v34
	v_lshlrev_b64 v[34:35], 9, v[34:35]
	v_lshl_add_u64 v[38:39], v[98:99], 0, v[34:35]
	global_load_dwordx4 v[34:37], v[38:39], off
	global_load_dwordx4 v[90:93], v[38:39], off offset:32
	global_load_dwordx4 v[86:89], v[38:39], off offset:64
	global_load_dwordx4 v[82:85], v[38:39], off offset:96
	s_mul_i32 s64, s70, 0x1f0
	v_or_b32_e32 v38, s71, v118
	v_add_u32_e32 v120, s64, v119
	s_mul_i32 s64, s70, 0x8020
	v_mul_hi_u32 v0, v38, s51
	s_bfe_u32 s64, s64, 0x3000d
	v_lshrrev_b32_e32 v0, 5, v0
	v_add_u32_e32 v39, s64, v111
	v_add_lshl_u32 v40, v0, v111, 12
	v_mul_i32_i24_e32 v42, 0xffffffd8, v0
	v_add_u32_e32 v0, v38, v104
	v_lshlrev_b32_e32 v122, 1, v113
	v_add3_u32 v44, v0, v42, v40
	v_lshl_or_b32 v0, v39, 13, v122
	v_lshl_add_u64 v[46:47], v[100:101], 0, v[0:1]
	global_load_dwordx2 v[74:75], v[46:47], off
	v_or_b32_e32 v46, s71, v110
	v_mov_b32_e32 v47, v1
	v_ashrrev_i32_e32 v43, 31, v42
	v_lshl_add_u64 v[46:47], v[46:47], 0, v[104:105]
	v_mov_b32_e32 v41, v1
	v_lshl_add_u64 v[42:43], v[46:47], 0, v[42:43]
	v_lshl_add_u64 v[40:41], v[42:43], 0, v[40:41]
	v_lshl_add_u64 v[40:41], v[40:41], 1, v[100:101]
	s_or_b32 s64, s71, 16
	global_load_dwordx2 v[76:77], v[40:41], off offset:16
	v_lshl_add_u64 v[40:41], v[102:103], 0, v[0:1]
	v_or_b32_e32 v0, s64, v118
	v_ashrrev_i32_e32 v45, 31, v44
	v_mul_hi_u32 v39, v0, s51
	global_load_dwordx2 v[66:67], v[40:41], off
	v_lshl_add_u64 v[40:41], v[44:45], 1, v[102:103]
	s_mulk_i32 s64, 0xcd
	v_lshrrev_b32_e32 v39, 5, v39
	global_load_dwordx2 v[68:69], v[40:41], off
	s_bfe_u32 s64, s64, 0x3000d
	v_add_lshl_u32 v40, v39, v111, 12
	v_mul_i32_i24_e32 v42, 0xffffffd8, v39
	v_mov_b32_e32 v39, v1
	v_add_lshl_u32 v41, v111, s64, 12
	v_add_u32_e32 v0, v0, v104
	v_ashrrev_i32_e32 v43, 31, v42
	v_lshl_add_u64 v[106:107], v[38:39], 0, v[104:105]
	v_or_b32_e32 v48, v41, v117
	v_add3_u32 v44, v0, v42, v40
	v_or_b32_e32 v0, v41, v113
	v_mov_b32_e32 v41, v1
	v_lshl_add_u64 v[38:39], v[106:107], 0, v[42:43]
	v_lshlrev_b32_e32 v0, 1, v0
	v_lshl_add_u64 v[38:39], v[38:39], 0, v[40:41]
	v_lshl_add_u64 v[46:47], v[100:101], 0, v[0:1]
	v_lshl_add_u64 v[38:39], v[38:39], 1, v[100:101]
	v_lshlrev_b32_e32 v0, 1, v48
	v_ashrrev_i32_e32 v45, 31, v44
	global_load_dwordx2 v[72:73], v[38:39], off offset:32
	v_lshl_add_u64 v[38:39], v[102:103], 0, v[0:1]
	global_load_dwordx2 v[70:71], v[46:47], off offset:32
	global_load_dwordx2 v[78:79], v[38:39], off
	v_lshl_add_u64 v[38:39], v[44:45], 1, v[102:103]
	global_load_dwordx2 v[80:81], v[38:39], off
	v_mov_b32_e32 v0, 0xff800000
	s_waitcnt vmcnt(0)
	v_mfma_f32_32x32x16_bf16 v[34:49], v[34:37], v[50:53], 0
	s_waitcnt vmcnt(10)
	v_mfma_f32_32x32x16_bf16 v[34:49], v[90:93], v[54:57], v[34:49]
	s_waitcnt vmcnt(9)
	v_mfma_f32_32x32x16_bf16 v[34:49], v[86:89], v[58:61], v[34:49]
	s_waitcnt vmcnt(8)
	v_mfma_f32_32x32x16_bf16 v[34:49], v[82:85], v[62:65], v[34:49]
	v_mov_b32_e32 v218, 0xff800000
	ds_read_b32 v202, v120 offset:928
	ds_read_b32 v203, v120 offset:932
	ds_read_b32 v204, v120 offset:936
	ds_read_b32 v205, v120 offset:940
	ds_read_b32 v206, v120 offset:960
	ds_read_b32 v207, v120 offset:964
	ds_read_b32 v208, v120 offset:968
	ds_read_b32 v209, v120 offset:972
	ds_read_b32 v210, v120 offset:992
	ds_read_b32 v211, v120 offset:996
	ds_read_b32 v212, v120 offset:1000
	ds_read_b32 v213, v120 offset:1004
	ds_read_b32 v214, v120 offset:1024
	ds_read_b32 v215, v120 offset:1028
	ds_read_b32 v216, v120 offset:1032
	ds_read_b32 v217, v120 offset:1036
	s_waitcnt lgkmcnt(0)
	v_add_f32_e32 v202, v34, v202
	v_add_f32_e32 v203, v35, v203
	v_add_f32_e32 v204, v36, v204
	v_add_f32_e32 v205, v37, v205
	v_add_f32_e32 v206, v38, v206
	v_add_f32_e32 v207, v39, v207
	v_add_f32_e32 v208, v40, v208
	v_add_f32_e32 v209, v41, v209
	v_add_f32_e32 v210, v42, v210
	v_add_f32_e32 v211, v43, v211
	v_add_f32_e32 v212, v44, v212
	v_add_f32_e32 v213, v45, v213
	v_add_f32_e32 v214, v46, v214
	v_add_f32_e32 v215, v47, v215
	v_add_f32_e32 v216, v48, v216
	v_add_f32_e32 v217, v49, v217
	v_cndmask_b32_e64 v82, v218, v202, s[0:1]
	v_cndmask_b32_e64 v0, v218, v203, s[4:5]
	v_cndmask_b32_e64 v35, v218, v204, s[6:7]
	v_cndmask_b32_e64 v34, v218, v205, s[8:9]
	v_cndmask_b32_e64 v86, v218, v206, s[10:11]
	v_cndmask_b32_e64 v37, v218, v207, s[12:13]
	v_cndmask_b32_e64 v88, v218, v208, s[14:15]
	v_cndmask_b32_e64 v89, v218, v209, s[16:17]
	v_cndmask_b32_e64 v90, v218, v210, s[18:19]
	v_cndmask_b32_e64 v41, v218, v211, s[20:21]
	v_cndmask_b32_e64 v43, v218, v212, s[22:23]
	v_cndmask_b32_e64 v42, v218, v213, s[24:25]
	v_cndmask_b32_e64 v38, v218, v214, s[26:27]
	v_cndmask_b32_e64 v36, v218, v215, s[28:29]
	v_cndmask_b32_e64 v40, v218, v216, s[30:31]
	v_cndmask_b32_e64 v39, v218, v217, s[34:35]
	s_mov_b32 s64, 0xff800000
	v_max3_f32 v44, v82, s64, v0
	v_max3_f32 v44, v44, v35, v34
	v_max3_f32 v44, v44, v86, v37
	v_max3_f32 v44, v44, v88, v89
	v_max3_f32 v44, v44, v90, v41
	v_max3_f32 v44, v44, v43, v42
	v_max3_f32 v44, v44, v38, v36
	v_max3_f32 v44, v44, v40, v39
	v_mov_b32_e32 v45, v44
	s_nop 1
	v_permlane32_swap_b32_e32 v44, v45
	v_max_f32_e32 v45, v45, v45
	v_max_f32_e32 v44, v44, v44
	v_max_f32_e32 v44, v44, v45
	v_sub_f32_e32 v45, v44, v121
	v_cmp_lt_f32_e32 vcc, s50, v45
	s_cbranch_vccz .LBB0_421
	v_max_f32_e32 v44, v44, v44
	v_max_f32_e32 v45, v121, v121
	v_max_f32_e32 v45, v45, v44
	v_sub_f32_e32 v44, v121, v45
	v_exp_f32_e32 v44, v44
	v_mov_b32_e32 v121, v45
	v_pk_mul_f32 v[32:33], v[32:33], v[44:45] op_sel_hi:[1,0]
	v_pk_mul_f32 v[30:31], v[30:31], v[44:45] op_sel_hi:[1,0]
	v_pk_mul_f32 v[28:29], v[28:29], v[44:45] op_sel_hi:[1,0]
	v_pk_mul_f32 v[26:27], v[26:27], v[44:45] op_sel_hi:[1,0]
	v_pk_mul_f32 v[24:25], v[24:25], v[44:45] op_sel_hi:[1,0]
	v_pk_mul_f32 v[22:23], v[22:23], v[44:45] op_sel_hi:[1,0]
	v_pk_mul_f32 v[20:21], v[20:21], v[44:45] op_sel_hi:[1,0]
	v_pk_mul_f32 v[18:19], v[18:19], v[44:45] op_sel_hi:[1,0]
	v_pk_mul_f32 v[16:17], v[16:17], v[44:45] op_sel_hi:[1,0]
	v_pk_mul_f32 v[14:15], v[14:15], v[44:45] op_sel_hi:[1,0]
	v_pk_mul_f32 v[12:13], v[12:13], v[44:45] op_sel_hi:[1,0]
	v_pk_mul_f32 v[10:11], v[10:11], v[44:45] op_sel_hi:[1,0]
	v_pk_mul_f32 v[8:9], v[8:9], v[44:45] op_sel_hi:[1,0]
	v_pk_mul_f32 v[6:7], v[6:7], v[44:45] op_sel_hi:[1,0]
	v_pk_mul_f32 v[4:5], v[4:5], v[44:45] op_sel_hi:[1,0]
	v_pk_mul_f32 v[2:3], v[2:3], v[44:45] op_sel_hi:[1,0]
	v_mul_f32_e32 v123, v123, v44
.LBB0_421:
	v_sub_f32_e32 v0, v0, v121
	v_exp_f32_e32 v83, v0
	v_sub_f32_e32 v0, v35, v121
	v_exp_f32_e32 v84, v0
	v_sub_f32_e32 v0, v34, v121
	v_exp_f32_e32 v85, v0
	v_sub_f32_e32 v0, v86, v121
	v_exp_f32_e32 v86, v0
	v_sub_f32_e32 v0, v37, v121
	v_exp_f32_e32 v87, v0
	v_sub_f32_e32 v0, v88, v121
	v_exp_f32_e32 v88, v0
	v_sub_f32_e32 v0, v89, v121
	v_exp_f32_e32 v89, v0
	v_sub_f32_e32 v0, v90, v121
	v_exp_f32_e32 v90, v0
	v_sub_f32_e32 v0, v41, v121
	v_exp_f32_e32 v91, v0
	v_sub_f32_e32 v0, v43, v121
	v_exp_f32_e32 v92, v0
	v_sub_f32_e32 v0, v42, v121
	s_add_i32 s64, s71, 32
	v_exp_f32_e32 v93, v0
	v_or_b32_e32 v0, s64, v109
	v_mul_hi_u32 v34, v0, s51
	v_lshrrev_b32_e32 v34, 5, v34
	v_mul_i32_i24_e32 v35, 0xffffffd8, v34
	v_add_lshl_u32 v34, v34, v111, 6
	v_add_u32_e32 v0, v0, v112
	v_add3_u32 v34, v0, v35, v34
	v_ashrrev_i32_e32 v35, 31, v34
	v_lshlrev_b64 v[34:35], 9, v[34:35]
	v_lshl_add_u64 v[132:133], v[98:99], 0, v[34:35]
	global_load_dwordx4 v[46:49], v[132:133], off
	v_sub_f32_e32 v44, v82, v121
	v_exp_f32_e32 v82, v44
	v_cvt_pk_bf16_f32 v43, v84, v85
	v_cvt_pk_bf16_f32 v44, v86, v87
	v_cvt_pk_bf16_f32 v45, v88, v89
	v_cvt_pk_bf16_f32 v42, v82, v83
	v_sub_f32_e32 v0, v38, v121
	v_exp_f32_e32 v124, v0
	s_waitcnt vmcnt(7)
	v_mfma_f32_32x32x16_bf16 v[2:17], v[74:77], v[42:45], v[2:17]
	global_load_dwordx4 v[74:77], v[132:133], off offset:32
	v_sub_f32_e32 v0, v36, v121
	v_exp_f32_e32 v125, v0
	v_sub_f32_e32 v0, v40, v121
	v_exp_f32_e32 v126, v0
	v_sub_f32_e32 v0, v39, v121
	v_exp_f32_e32 v127, v0
	s_waitcnt vmcnt(6)
	v_mfma_f32_32x32x16_bf16 v[18:33], v[66:69], v[42:45], v[18:33]
	v_cvt_pk_bf16_f32 v34, v90, v91
	v_cvt_pk_bf16_f32 v35, v92, v93
	v_cvt_pk_bf16_f32 v36, v124, v125
	v_cvt_pk_bf16_f32 v37, v126, v127
	v_or_b32_e32 v0, s64, v118
	global_load_dwordx4 v[128:131], v[132:133], off offset:64
	s_mulk_i32 s64, 0xcd
	s_waitcnt vmcnt(5)
	v_mfma_f32_32x32x16_bf16 v[2:17], v[70:73], v[34:37], v[2:17]
	s_bfe_u32 s64, s64, 0x3000d
	global_load_dwordx4 v[132:135], v[132:133], off offset:96
	s_mul_i32 s70, s71, 0xcd
	s_waitcnt vmcnt(4)
	v_mfma_f32_32x32x16_bf16 v[18:33], v[78:81], v[34:37], v[18:33]
	v_mul_hi_u32 v34, v0, s51
	v_lshrrev_b32_e32 v35, 5, v34
	v_add_lshl_u32 v37, v111, s64, 12
	v_add_lshl_u32 v34, v35, v111, 12
	v_mul_i32_i24_e32 v36, 0xffffffd8, v35
	v_add_u32_e32 v0, v0, v104
	v_or_b32_e32 v42, v37, v114
	v_add3_u32 v38, v0, v36, v34
	v_or_b32_e32 v0, v37, v113
	v_ashrrev_i32_e32 v37, 31, v36
	v_lshlrev_b32_e32 v0, 1, v0
	v_mov_b32_e32 v35, v1
	v_lshl_add_u64 v[36:37], v[106:107], 0, v[36:37]
	v_lshl_add_u64 v[40:41], v[100:101], 0, v[0:1]
	v_lshl_add_u64 v[34:35], v[36:37], 0, v[34:35]
	v_lshlrev_b32_e32 v0, 1, v42
	s_add_i32 s64, s71, 48
	v_ashrrev_i32_e32 v39, 31, v38
	v_lshl_add_u64 v[34:35], v[34:35], 1, v[100:101]
	v_lshl_add_u64 v[36:37], v[102:103], 0, v[0:1]
	v_or_b32_e32 v0, s64, v118
	v_lshl_add_u64 v[38:39], v[38:39], 1, v[102:103]
	global_load_dwordx2 v[66:67], v[40:41], off offset:64
	global_load_dwordx2 v[68:69], v[34:35], off offset:64
	global_load_dwordx2 v[70:71], v[36:37], off
	global_load_dwordx2 v[72:73], v[38:39], off
	v_mul_hi_u32 v34, v0, s51
	v_lshrrev_b32_e32 v78, 5, v34
	s_add_i32 s64, s70, 0x2670
	s_bfe_u32 s64, s64, 0x3000d
	v_add_lshl_u32 v79, v111, s64, 12
	v_add_lshl_u32 v81, v78, v111, 12
	v_mul_i32_i24_e32 v78, 0xffffffd8, v78
	v_add_u32_e32 v0, v0, v104
	v_or_b32_e32 v80, v79, v115
	v_add3_u32 v0, v0, v78, v81
	v_or_b32_e32 v78, v79, v113
	v_lshlrev_b32_e32 v78, 1, v78
	v_mov_b32_e32 v79, v1
	s_waitcnt vmcnt(7)
	v_mfma_f32_32x32x16_bf16 v[34:49], v[46:49], v[50:53], 0
	s_waitcnt vmcnt(6)
	v_mfma_f32_32x32x16_bf16 v[34:49], v[74:77], v[54:57], v[34:49]
	v_lshlrev_b64 v[76:77], 1, v[0:1]
	v_lshlrev_b32_e32 v0, 1, v80
	v_lshl_add_u64 v[74:75], v[100:101], 0, v[78:79]
	v_lshl_add_u64 v[78:79], v[100:101], 0, v[76:77]
	v_lshl_add_u64 v[80:81], v[102:103], 0, v[0:1]
	v_lshl_add_u64 v[106:107], v[102:103], 0, v[76:77]
	global_load_dwordx2 v[74:75], v[74:75], off offset:16
	s_nop 0
	global_load_dwordx2 v[76:77], v[78:79], off
	s_nop 0
	global_load_dwordx2 v[78:79], v[80:81], off
	s_nop 0
	global_load_dwordx2 v[80:81], v[106:107], off
	s_waitcnt vmcnt(9)
	v_mfma_f32_32x32x16_bf16 v[34:49], v[128:131], v[58:61], v[34:49]
	v_mov_b32_e32 v0, 0xff800000
	v_mov_b32_e32 v107, 0xff800000
	s_waitcnt vmcnt(8)
	v_mfma_f32_32x32x16_bf16 v[34:49], v[132:135], v[62:65], v[34:49]
	v_mov_b32_e32 v218, 0xff800000
	ds_read_b32 v202, v120 offset:1056
	ds_read_b32 v203, v120 offset:1060
	ds_read_b32 v204, v120 offset:1064
	ds_read_b32 v205, v120 offset:1068
	ds_read_b32 v206, v120 offset:1052
	ds_read_b32 v207, v120 offset:1056
	ds_read_b32 v208, v120 offset:1060
	ds_read_b32 v209, v120 offset:1064
	ds_read_b32 v210, v120 offset:1084
	ds_read_b32 v211, v120 offset:1088
	ds_read_b32 v212, v120 offset:1092
	ds_read_b32 v213, v120 offset:1096
	ds_read_b32 v214, v120 offset:1116
	ds_read_b32 v215, v120 offset:1120
	ds_read_b32 v216, v120 offset:1124
	ds_read_b32 v217, v120 offset:1128
	s_waitcnt lgkmcnt(0)
	v_add_f32_e32 v202, v34, v202
	v_add_f32_e32 v203, v35, v203
	v_add_f32_e32 v204, v36, v204
	v_add_f32_e32 v205, v37, v205
	v_add_f32_e32 v206, v38, v206
	v_add_f32_e32 v207, v39, v207
	v_add_f32_e32 v208, v40, v208
	v_add_f32_e32 v209, v41, v209
	v_add_f32_e32 v210, v42, v210
	v_add_f32_e32 v211, v43, v211
	v_add_f32_e32 v212, v44, v212
	v_add_f32_e32 v213, v45, v213
	v_add_f32_e32 v214, v46, v214
	v_add_f32_e32 v215, v47, v215
	v_add_f32_e32 v216, v48, v216
	v_add_f32_e32 v217, v49, v217
	v_cndmask_b32_e64 v107, v218, v202, s[36:37]
	v_cndmask_b32_e64 v0, v218, v203, s[38:39]
	v_cndmask_b32_e64 v35, v218, v204, s[40:41]
	v_cndmask_b32_e64 v34, v218, v205, s[42:43]
	v_cndmask_b32_e64 v37, v218, v206, s[0:1]
	v_cndmask_b32_e64 v36, v218, v207, s[4:5]
	v_cndmask_b32_e64 v39, v218, v208, s[6:7]
	v_cndmask_b32_e64 v38, v218, v209, s[8:9]
	v_cndmask_b32_e64 v41, v218, v210, s[10:11]
	v_cndmask_b32_e64 v40, v218, v211, s[12:13]
	v_cndmask_b32_e64 v43, v218, v212, s[14:15]
	v_cndmask_b32_e64 v42, v218, v213, s[16:17]
	v_cndmask_b32_e64 v45, v218, v214, s[18:19]
	v_cndmask_b32_e64 v44, v218, v215, s[20:21]
	v_cndmask_b32_e64 v47, v218, v216, s[22:23]
	v_cndmask_b32_e64 v46, v218, v217, s[24:25]
	v_add_f32_e32 v49, 0, v82
	v_add_f32_e32 v49, v83, v49
	v_add_f32_e32 v49, v84, v49
	v_add_f32_e32 v49, v85, v49
	v_add_f32_e32 v49, v86, v49
	v_add_f32_e32 v49, v87, v49
	v_add_f32_e32 v49, v88, v49
	s_mov_b32 s64, 0xff800000
	v_add_f32_e32 v49, v89, v49
	v_max3_f32 v48, v107, s64, v0
	v_add_f32_e32 v49, v90, v49
	v_max3_f32 v48, v48, v35, v34
	v_add_f32_e32 v49, v91, v49
	v_max3_f32 v48, v48, v37, v36
	v_add_f32_e32 v49, v92, v49
	v_max3_f32 v48, v48, v39, v38
	v_add_f32_e32 v49, v93, v49
	v_max3_f32 v48, v48, v41, v40
	v_add_f32_e32 v49, v124, v49
	v_max3_f32 v48, v48, v43, v42
	v_add_f32_e32 v49, v125, v49
	v_max3_f32 v48, v48, v45, v44
	v_add_f32_e32 v49, v126, v49
	v_add_f32_e32 v49, v127, v49
	v_max3_f32 v48, v48, v47, v46
	v_add_f32_e32 v106, v123, v49
	v_mov_b32_e32 v49, v48
	s_nop 1
	v_permlane32_swap_b32_e32 v48, v49
	v_max_f32_e32 v49, v49, v49
	v_max_f32_e32 v48, v48, v48
	v_max_f32_e32 v48, v48, v49
	v_sub_f32_e32 v49, v48, v121
	v_cmp_lt_f32_e32 vcc, s50, v49
	s_cbranch_vccz .LBB0_455
	v_max_f32_e32 v48, v48, v48
	v_max_f32_e32 v49, v121, v121
	v_max_f32_e32 v49, v49, v48
	v_sub_f32_e32 v48, v121, v49
	v_exp_f32_e32 v48, v48
	v_mov_b32_e32 v121, v49
	v_pk_mul_f32 v[16:17], v[16:17], v[48:49] op_sel_hi:[1,0]
	v_pk_mul_f32 v[14:15], v[14:15], v[48:49] op_sel_hi:[1,0]
	v_pk_mul_f32 v[12:13], v[12:13], v[48:49] op_sel_hi:[1,0]
	v_pk_mul_f32 v[10:11], v[10:11], v[48:49] op_sel_hi:[1,0]
	v_pk_mul_f32 v[8:9], v[8:9], v[48:49] op_sel_hi:[1,0]
	v_pk_mul_f32 v[6:7], v[6:7], v[48:49] op_sel_hi:[1,0]
	v_pk_mul_f32 v[4:5], v[4:5], v[48:49] op_sel_hi:[1,0]
	v_pk_mul_f32 v[2:3], v[2:3], v[48:49] op_sel_hi:[1,0]
	v_pk_mul_f32 v[32:33], v[32:33], v[48:49] op_sel_hi:[1,0]
	v_pk_mul_f32 v[30:31], v[30:31], v[48:49] op_sel_hi:[1,0]
	v_pk_mul_f32 v[28:29], v[28:29], v[48:49] op_sel_hi:[1,0]
	v_pk_mul_f32 v[26:27], v[26:27], v[48:49] op_sel_hi:[1,0]
	v_pk_mul_f32 v[24:25], v[24:25], v[48:49] op_sel_hi:[1,0]
	v_pk_mul_f32 v[22:23], v[22:23], v[48:49] op_sel_hi:[1,0]
	v_pk_mul_f32 v[20:21], v[20:21], v[48:49] op_sel_hi:[1,0]
	v_pk_mul_f32 v[18:19], v[18:19], v[48:49] op_sel_hi:[1,0]
	v_mul_f32_e32 v106, v106, v48
.LBB0_455:
	v_sub_f32_e32 v0, v0, v121
	v_exp_f32_e32 v123, v0
	v_sub_f32_e32 v0, v35, v121
	v_exp_f32_e32 v124, v0
	v_sub_f32_e32 v0, v34, v121
	v_exp_f32_e32 v125, v0
	v_sub_f32_e32 v0, v37, v121
	v_exp_f32_e32 v126, v0
	v_sub_f32_e32 v0, v36, v121
	v_exp_f32_e32 v127, v0
	v_sub_f32_e32 v0, v39, v121
	v_sub_f32_e32 v48, v107, v121
	v_exp_f32_e32 v128, v0
	v_sub_f32_e32 v0, v38, v121
	v_exp_f32_e32 v107, v48
	v_exp_f32_e32 v129, v0
	v_sub_f32_e32 v0, v41, v121
	v_exp_f32_e32 v130, v0
	v_sub_f32_e32 v0, v40, v121
	v_exp_f32_e32 v131, v0
	v_sub_f32_e32 v0, v43, v121
	v_exp_f32_e32 v132, v0
	v_sub_f32_e32 v0, v42, v121
	v_exp_f32_e32 v133, v0
	v_sub_f32_e32 v0, v45, v121
	v_cvt_pk_bf16_f32 v34, v107, v123
	v_cvt_pk_bf16_f32 v35, v124, v125
	v_cvt_pk_bf16_f32 v36, v126, v127
	v_cvt_pk_bf16_f32 v37, v128, v129
	v_exp_f32_e32 v134, v0
	v_sub_f32_e32 v0, v44, v121
	s_waitcnt vmcnt(6)
	v_mfma_f32_32x32x16_bf16 v[2:17], v[66:69], v[34:37], v[2:17]
	v_exp_f32_e32 v135, v0
	v_sub_f32_e32 v0, v47, v121
	v_exp_f32_e32 v136, v0
	v_sub_f32_e32 v0, v46, v121
	v_exp_f32_e32 v137, v0
	s_add_i32 s64, s71, 64
	v_or_b32_e32 v0, s64, v109
	s_waitcnt vmcnt(4)
	v_mfma_f32_32x32x16_bf16 v[18:33], v[70:73], v[34:37], v[18:33]
	v_cvt_pk_bf16_f32 v34, v130, v131
	v_cvt_pk_bf16_f32 v35, v132, v133
	v_cvt_pk_bf16_f32 v36, v134, v135
	v_cvt_pk_bf16_f32 v37, v136, v137
	s_addk_i32 s70, 0x4010
	s_waitcnt vmcnt(2)
	v_mfma_f32_32x32x16_bf16 v[2:17], v[74:77], v[34:37], v[2:17]
	s_waitcnt vmcnt(0)
	v_mfma_f32_32x32x16_bf16 v[18:33], v[78:81], v[34:37], v[18:33]
	v_mul_hi_u32 v34, v0, s51
	v_lshrrev_b32_e32 v34, 5, v34
	v_mul_i32_i24_e32 v35, 0xffffffd8, v34
	v_add_lshl_u32 v34, v34, v111, 6
	v_add_u32_e32 v0, v0, v112
	v_add3_u32 v34, v0, v35, v34
	v_ashrrev_i32_e32 v35, 31, v34
	v_lshlrev_b64 v[34:35], 9, v[34:35]
	v_lshl_add_u64 v[38:39], v[98:99], 0, v[34:35]
	global_load_dwordx4 v[34:37], v[38:39], off
	global_load_dwordx4 v[90:93], v[38:39], off offset:32
	global_load_dwordx4 v[86:89], v[38:39], off offset:64
	global_load_dwordx4 v[82:85], v[38:39], off offset:96
	v_or_b32_e32 v0, s64, v118
	s_mulk_i32 s64, 0xcd
	v_mul_hi_u32 v38, v0, s51
	s_bfe_u32 s64, s64, 0x3000d
	v_lshrrev_b32_e32 v38, 5, v38
	v_add_lshl_u32 v39, v111, s64, 12
	v_add_lshl_u32 v40, v38, v111, 12
	v_mul_i32_i24_e32 v38, 0xffffffd8, v38
	v_add_u32_e32 v0, v0, v104
	v_add3_u32 v0, v0, v38, v40
	v_or_b32_e32 v38, v39, v113
	v_or_b32_e32 v42, v39, v116
	v_lshlrev_b32_e32 v38, 1, v38
	v_mov_b32_e32 v39, v1
	v_lshl_add_u64 v[38:39], v[100:101], 0, v[38:39]
	global_load_dwordx2 v[70:71], v[38:39], off offset:48
	v_lshlrev_b64 v[38:39], 1, v[0:1]
	v_lshl_add_u64 v[40:41], v[100:101], 0, v[38:39]
	v_lshlrev_b32_e32 v0, 1, v42
	v_lshl_add_u64 v[38:39], v[102:103], 0, v[38:39]
	s_add_i32 s64, s71, 0x50
	global_load_dwordx2 v[72:73], v[40:41], off
	global_load_dwordx2 v[68:69], v[38:39], off
	v_lshl_add_u64 v[40:41], v[102:103], 0, v[0:1]
	v_or_b32_e32 v0, s64, v118
	v_mul_hi_u32 v38, v0, s51
	s_bfe_u32 s64, s70, 0x3000d
	v_lshrrev_b32_e32 v38, 5, v38
	global_load_dwordx2 v[66:67], v[40:41], off
	v_add_u32_e32 v39, s64, v111
	v_add_lshl_u32 v40, v38, v111, 12
	v_mul_i32_i24_e32 v38, 0xffffffd8, v38
	v_add_u32_e32 v0, v0, v104
	v_add3_u32 v0, v0, v38, v40
	v_lshl_or_b32 v38, v39, 13, v122
	v_mov_b32_e32 v39, v1
	v_lshl_add_u64 v[40:41], v[100:101], 0, v[38:39]
	v_lshl_add_u64 v[38:39], v[102:103], 0, v[38:39]
	global_load_dwordx2 v[78:79], v[40:41], off
	global_load_dwordx2 v[74:75], v[38:39], off
	v_lshlrev_b64 v[40:41], 1, v[0:1]
	v_lshl_add_u64 v[42:43], v[100:101], 0, v[40:41]
	v_lshl_add_u64 v[38:39], v[102:103], 0, v[40:41]
	global_load_dwordx2 v[80:81], v[42:43], off
	global_load_dwordx2 v[76:77], v[38:39], off
	s_waitcnt vmcnt(11)
	v_mfma_f32_32x32x16_bf16 v[34:49], v[34:37], v[50:53], 0
	s_waitcnt vmcnt(10)
	v_mfma_f32_32x32x16_bf16 v[34:49], v[90:93], v[54:57], v[34:49]
	s_waitcnt vmcnt(9)
	v_mfma_f32_32x32x16_bf16 v[34:49], v[86:89], v[58:61], v[34:49]
	s_waitcnt vmcnt(8)
	v_mfma_f32_32x32x16_bf16 v[34:49], v[82:85], v[62:65], v[34:49]
	v_mov_b32_e32 v218, 0xff800000
	ds_read_b32 v202, v120 offset:1148
	ds_read_b32 v203, v120 offset:1152
	ds_read_b32 v204, v120 offset:1156
	ds_read_b32 v205, v120 offset:1160
	ds_read_b32 v206, v120 offset:1180
	ds_read_b32 v207, v120 offset:1184
	ds_read_b32 v208, v120 offset:1188
	ds_read_b32 v209, v120 offset:1192
	ds_read_b32 v210, v120 offset:1176
	ds_read_b32 v211, v120 offset:1180
	ds_read_b32 v212, v120 offset:1184
	ds_read_b32 v213, v120 offset:1188
	ds_read_b32 v214, v120 offset:1208
	ds_read_b32 v215, v120 offset:1212
	ds_read_b32 v216, v120 offset:1216
	ds_read_b32 v217, v120 offset:1220
	s_waitcnt lgkmcnt(0)
	v_add_f32_e32 v202, v34, v202
	v_add_f32_e32 v203, v35, v203
	v_add_f32_e32 v204, v36, v204
	v_add_f32_e32 v205, v37, v205
	v_add_f32_e32 v206, v38, v206
	v_add_f32_e32 v207, v39, v207
	v_add_f32_e32 v208, v40, v208
	v_add_f32_e32 v209, v41, v209
	v_add_f32_e32 v210, v42, v210
	v_add_f32_e32 v211, v43, v211
	v_add_f32_e32 v212, v44, v212
	v_add_f32_e32 v213, v45, v213
	v_add_f32_e32 v214, v46, v214
	v_add_f32_e32 v215, v47, v215
	v_add_f32_e32 v216, v48, v216
	v_add_f32_e32 v217, v49, v217
	v_cndmask_b32_e64 v83, v218, v202, s[26:27]
	v_cndmask_b32_e64 v82, v218, v203, s[28:29]
	v_cndmask_b32_e64 v85, v218, v204, s[30:31]
	v_cndmask_b32_e64 v84, v218, v205, s[34:35]
	v_cndmask_b32_e64 v86, v218, v206, s[36:37]
	v_cndmask_b32_e64 v37, v218, v207, s[38:39]
	v_cndmask_b32_e64 v39, v218, v208, s[40:41]
	v_cndmask_b32_e64 v38, v218, v209, s[42:43]
	v_cndmask_b32_e64 v41, v218, v210, s[0:1]
	v_cndmask_b32_e64 v40, v218, v211, s[4:5]
	v_cndmask_b32_e64 v43, v218, v212, s[6:7]
	v_cndmask_b32_e64 v42, v218, v213, s[8:9]
	v_cndmask_b32_e64 v34, v218, v214, s[10:11]
	v_cndmask_b32_e64 v0, v218, v215, s[12:13]
	v_cndmask_b32_e64 v36, v218, v216, s[14:15]
	v_cndmask_b32_e64 v35, v218, v217, s[16:17]
	v_add_f32_e32 v45, 0, v107
	v_add_f32_e32 v45, v123, v45
	v_add_f32_e32 v45, v124, v45
	v_add_f32_e32 v45, v125, v45
	v_add_f32_e32 v45, v126, v45
	v_add_f32_e32 v45, v127, v45
	v_add_f32_e32 v45, v128, v45
	s_mov_b32 s64, 0xff800000
	v_add_f32_e32 v45, v129, v45
	v_max3_f32 v44, v83, s64, v82
	v_add_f32_e32 v45, v130, v45
	v_max3_f32 v44, v44, v85, v84
	v_add_f32_e32 v45, v131, v45
	v_max3_f32 v44, v44, v86, v37
	v_add_f32_e32 v45, v132, v45
	v_max3_f32 v44, v44, v39, v38
	v_add_f32_e32 v45, v133, v45
	v_max3_f32 v44, v44, v41, v40
	v_add_f32_e32 v45, v134, v45
	v_max3_f32 v44, v44, v43, v42
	v_add_f32_e32 v45, v135, v45
	v_max3_f32 v44, v44, v34, v0
	v_add_f32_e32 v45, v136, v45
	v_add_f32_e32 v45, v137, v45
	v_max3_f32 v44, v44, v36, v35
	v_add_f32_e32 v90, v106, v45
	v_mov_b32_e32 v45, v44
	s_nop 1
	v_permlane32_swap_b32_e32 v44, v45
	v_max_f32_e32 v45, v45, v45
	v_max_f32_e32 v44, v44, v44
	v_max_f32_e32 v44, v44, v45
	v_sub_f32_e32 v45, v44, v121
	v_cmp_lt_f32_e32 vcc, s50, v45
	s_cbranch_vccz .LBB0_489
	v_max_f32_e32 v44, v44, v44
	v_max_f32_e32 v45, v121, v121
	v_max_f32_e32 v45, v45, v44
	v_sub_f32_e32 v44, v121, v45
	v_exp_f32_e32 v44, v44
	v_mov_b32_e32 v121, v45
	v_pk_mul_f32 v[16:17], v[16:17], v[44:45] op_sel_hi:[1,0]
	v_pk_mul_f32 v[14:15], v[14:15], v[44:45] op_sel_hi:[1,0]
	v_pk_mul_f32 v[12:13], v[12:13], v[44:45] op_sel_hi:[1,0]
	v_pk_mul_f32 v[10:11], v[10:11], v[44:45] op_sel_hi:[1,0]
	v_pk_mul_f32 v[8:9], v[8:9], v[44:45] op_sel_hi:[1,0]
	v_pk_mul_f32 v[6:7], v[6:7], v[44:45] op_sel_hi:[1,0]
	v_pk_mul_f32 v[4:5], v[4:5], v[44:45] op_sel_hi:[1,0]
	v_pk_mul_f32 v[2:3], v[2:3], v[44:45] op_sel_hi:[1,0]
	v_pk_mul_f32 v[32:33], v[32:33], v[44:45] op_sel_hi:[1,0]
	v_pk_mul_f32 v[30:31], v[30:31], v[44:45] op_sel_hi:[1,0]
	v_pk_mul_f32 v[28:29], v[28:29], v[44:45] op_sel_hi:[1,0]
	v_pk_mul_f32 v[26:27], v[26:27], v[44:45] op_sel_hi:[1,0]
	v_pk_mul_f32 v[24:25], v[24:25], v[44:45] op_sel_hi:[1,0]
	v_pk_mul_f32 v[22:23], v[22:23], v[44:45] op_sel_hi:[1,0]
	v_pk_mul_f32 v[20:21], v[20:21], v[44:45] op_sel_hi:[1,0]
	v_pk_mul_f32 v[18:19], v[18:19], v[44:45] op_sel_hi:[1,0]
	v_mul_f32_e32 v90, v90, v44
.LBB0_489:
	v_sub_f32_e32 v37, v37, v121
	v_exp_f32_e32 v122, v37
	v_sub_f32_e32 v37, v39, v121
	v_exp_f32_e32 v123, v37
	v_sub_f32_e32 v37, v38, v121
	v_exp_f32_e32 v124, v37
	v_sub_f32_e32 v37, v41, v121
	v_exp_f32_e32 v125, v37
	v_sub_f32_e32 v37, v40, v121
	v_exp_f32_e32 v126, v37
	v_sub_f32_e32 v37, v43, v121
	v_exp_f32_e32 v127, v37
	v_sub_f32_e32 v37, v42, v121
	s_add_i32 s64, s71, 0x60
	v_exp_f32_e32 v128, v37
	v_or_b32_e32 v37, s64, v109
	v_mul_hi_u32 v42, v37, s51
	v_lshrrev_b32_e32 v42, 5, v42
	v_sub_f32_e32 v44, v83, v121
	v_mul_i32_i24_e32 v43, 0xffffffd8, v42
	v_add_lshl_u32 v42, v42, v111, 6
	v_add_u32_e32 v37, v37, v112
	v_exp_f32_e32 v91, v44
	v_sub_f32_e32 v44, v82, v121
	v_add3_u32 v42, v37, v43, v42
	v_exp_f32_e32 v92, v44
	v_sub_f32_e32 v44, v85, v121
	v_ashrrev_i32_e32 v43, 31, v42
	v_exp_f32_e32 v93, v44
	v_sub_f32_e32 v44, v84, v121
	v_lshlrev_b64 v[42:43], 9, v[42:43]
	v_exp_f32_e32 v106, v44
	v_sub_f32_e32 v44, v86, v121
	v_lshl_add_u64 v[46:47], v[98:99], 0, v[42:43]
	v_exp_f32_e32 v107, v44
	global_load_dwordx4 v[42:45], v[46:47], off
	global_load_dwordx4 v[82:85], v[46:47], off offset:32
	v_cvt_pk_bf16_f32 v38, v91, v92
	v_cvt_pk_bf16_f32 v39, v93, v106
	v_cvt_pk_bf16_f32 v40, v107, v122
	v_cvt_pk_bf16_f32 v41, v123, v124
	v_sub_f32_e32 v0, v0, v121
	v_exp_f32_e32 v130, v0
	s_waitcnt vmcnt(8)
	v_mfma_f32_32x32x16_bf16 v[2:17], v[70:73], v[38:41], v[2:17]
	v_sub_f32_e32 v0, v36, v121
	v_sub_f32_e32 v34, v34, v121
	v_exp_f32_e32 v131, v0
	v_sub_f32_e32 v0, v35, v121
	v_exp_f32_e32 v129, v34
	v_exp_f32_e32 v132, v0
	v_cvt_pk_bf16_f32 v34, v125, v126
	s_waitcnt vmcnt(6)
	v_mfma_f32_32x32x16_bf16 v[18:33], v[66:69], v[38:41], v[18:33]
	v_cvt_pk_bf16_f32 v35, v127, v128
	v_cvt_pk_bf16_f32 v36, v129, v130
	v_cvt_pk_bf16_f32 v37, v131, v132
	s_mul_i32 s70, s71, 0xcccd
	v_or_b32_e32 v0, s64, v118
	s_add_i32 s64, s70, 0x4ccce0
	s_lshr_b32 s64, s64, 21
	s_waitcnt vmcnt(3)
	v_mfma_f32_32x32x16_bf16 v[2:17], v[78:81], v[34:37], v[2:17]
	global_load_dwordx4 v[78:81], v[46:47], off offset:64
	global_load_dwordx4 v[86:89], v[46:47], off offset:96
	s_waitcnt vmcnt(4)
	v_mfma_f32_32x32x16_bf16 v[18:33], v[74:77], v[34:37], v[18:33]
	v_mul_hi_u32 v34, v0, s51
	v_lshrrev_b32_e32 v34, 5, v34
	v_add_lshl_u32 v35, v111, s64, 12
	v_add_lshl_u32 v36, v34, v111, 12
	v_mul_i32_i24_e32 v34, 0xffffffd8, v34
	v_add_u32_e32 v0, v0, v104
	v_add3_u32 v0, v0, v34, v36
	v_or_b32_e32 v34, v35, v113
	v_or_b32_e32 v38, v35, v117
	v_lshlrev_b32_e32 v34, 1, v34
	v_mov_b32_e32 v35, v1
	v_lshl_add_u64 v[34:35], v[100:101], 0, v[34:35]
	global_load_dwordx2 v[66:67], v[34:35], off offset:32
	v_lshlrev_b64 v[34:35], 1, v[0:1]
	v_lshl_add_u64 v[36:37], v[100:101], 0, v[34:35]
	v_lshlrev_b32_e32 v0, 1, v38
	v_lshl_add_u64 v[34:35], v[102:103], 0, v[34:35]
	s_add_i32 s64, s71, 0x70
	global_load_dwordx2 v[68:69], v[36:37], off
	global_load_dwordx2 v[72:73], v[34:35], off
	v_lshl_add_u64 v[36:37], v[102:103], 0, v[0:1]
	v_or_b32_e32 v0, s64, v118
	v_mul_hi_u32 v34, v0, s51
	v_lshrrev_b32_e32 v34, 5, v34
	global_load_dwordx2 v[70:71], v[36:37], off
	v_add_lshl_u32 v75, v34, v111, 12
	v_mul_i32_i24_e32 v76, 0xffffffd8, v34
	s_add_i32 s64, s70, 0x5999b0
	s_lshr_b32 s64, s64, 21
	v_add_lshl_u32 v74, v111, s64, 12
	v_add_u32_e32 v0, v0, v104
	s_waitcnt vmcnt(7)
	v_mfma_f32_32x32x16_bf16 v[34:49], v[42:45], v[50:53], 0
	v_or_b32_e32 v133, v74, v114
	v_add3_u32 v0, v0, v76, v75
	v_or_b32_e32 v74, v74, v113
	v_lshlrev_b32_e32 v74, 1, v74
	v_mov_b32_e32 v75, v1
	v_lshl_add_u64 v[74:75], v[100:101], 0, v[74:75]
	global_load_dwordx2 v[74:75], v[74:75], off offset:64
	s_waitcnt vmcnt(7)
	v_mfma_f32_32x32x16_bf16 v[34:49], v[82:85], v[54:57], v[34:49]
	v_lshlrev_b64 v[84:85], 1, v[0:1]
	v_lshlrev_b32_e32 v0, 1, v133
	v_lshl_add_u64 v[76:77], v[100:101], 0, v[84:85]
	v_lshl_add_u64 v[82:83], v[102:103], 0, v[0:1]
	v_lshl_add_u64 v[84:85], v[102:103], 0, v[84:85]
	global_load_dwordx2 v[76:77], v[76:77], off
	v_mov_b32_e32 v0, 0xff800000
	global_load_dwordx2 v[82:83], v[82:83], off
	s_waitcnt vmcnt(8)
	v_mfma_f32_32x32x16_bf16 v[34:49], v[78:81], v[58:61], v[34:49]
	global_load_dwordx2 v[84:85], v[84:85], off
	v_mov_b32_e32 v78, 0xff800000
	s_waitcnt vmcnt(8)
	v_mfma_f32_32x32x16_bf16 v[34:49], v[86:89], v[62:65], v[34:49]
	v_mov_b32_e32 v218, 0xff800000
	ds_read_b32 v202, v120 offset:1240
	ds_read_b32 v203, v120 offset:1244
	ds_read_b32 v204, v120 offset:1248
	ds_read_b32 v205, v120 offset:1252
	ds_read_b32 v206, v120 offset:1272
	ds_read_b32 v207, v120 offset:1276
	ds_read_b32 v208, v120 offset:1280
	ds_read_b32 v209, v120 offset:1284
	ds_read_b32 v210, v120 offset:1304
	ds_read_b32 v211, v120 offset:1308
	ds_read_b32 v212, v120 offset:1312
	ds_read_b32 v213, v120 offset:1316
	ds_read_b32 v214, v120 offset:1300
	ds_read_b32 v215, v120 offset:1304
	ds_read_b32 v216, v120 offset:1308
	ds_read_b32 v217, v120 offset:1312
	s_waitcnt lgkmcnt(0)
	v_add_f32_e32 v202, v34, v202
	v_add_f32_e32 v203, v35, v203
	v_add_f32_e32 v204, v36, v204
	v_add_f32_e32 v205, v37, v205
	v_add_f32_e32 v206, v38, v206
	v_add_f32_e32 v207, v39, v207
	v_add_f32_e32 v208, v40, v208
	v_add_f32_e32 v209, v41, v209
	v_add_f32_e32 v210, v42, v210
	v_add_f32_e32 v211, v43, v211
	v_add_f32_e32 v212, v44, v212
	v_add_f32_e32 v213, v45, v213
	v_add_f32_e32 v214, v46, v214
	v_add_f32_e32 v215, v47, v215
	v_add_f32_e32 v216, v48, v216
	v_add_f32_e32 v217, v49, v217
	v_cndmask_b32_e64 v78, v218, v202, s[18:19]
	v_cndmask_b32_e64 v0, v218, v203, s[20:21]
	v_cndmask_b32_e64 v35, v218, v204, s[22:23]
	v_cndmask_b32_e64 v34, v218, v205, s[24:25]
	v_cndmask_b32_e64 v37, v218, v206, s[26:27]
	v_cndmask_b32_e64 v36, v218, v207, s[28:29]
	v_cndmask_b32_e64 v39, v218, v208, s[30:31]
	v_cndmask_b32_e64 v38, v218, v209, s[34:35]
	v_cndmask_b32_e64 v41, v218, v210, s[36:37]
	v_cndmask_b32_e64 v40, v218, v211, s[38:39]
	v_cndmask_b32_e64 v43, v218, v212, s[40:41]
	v_cndmask_b32_e64 v42, v218, v213, s[42:43]
	v_cndmask_b32_e64 v45, v218, v214, s[0:1]
	v_cndmask_b32_e64 v44, v218, v215, s[4:5]
	v_cndmask_b32_e64 v47, v218, v216, s[6:7]
	v_cndmask_b32_e64 v46, v218, v217, s[8:9]
	v_add_f32_e32 v49, 0, v91
	v_add_f32_e32 v49, v92, v49
	v_add_f32_e32 v49, v93, v49
	v_add_f32_e32 v49, v106, v49
	v_add_f32_e32 v49, v107, v49
	v_add_f32_e32 v49, v122, v49
	v_add_f32_e32 v49, v123, v49
	s_mov_b32 s64, 0xff800000
	v_add_f32_e32 v49, v124, v49
	v_max3_f32 v48, v78, s64, v0
	v_add_f32_e32 v49, v125, v49
	v_max3_f32 v48, v48, v35, v34
	v_add_f32_e32 v49, v126, v49
	v_max3_f32 v48, v48, v37, v36
	v_add_f32_e32 v49, v127, v49
	v_max3_f32 v48, v48, v39, v38
	v_add_f32_e32 v49, v128, v49
	v_max3_f32 v48, v48, v41, v40
	v_add_f32_e32 v49, v129, v49
	v_max3_f32 v48, v48, v43, v42
	v_add_f32_e32 v49, v130, v49
	v_max3_f32 v48, v48, v45, v44
	v_add_f32_e32 v49, v131, v49
	v_add_f32_e32 v49, v132, v49
	v_max3_f32 v48, v48, v47, v46
	v_add_f32_e32 v106, v90, v49
	v_mov_b32_e32 v49, v48
	s_nop 1
	v_permlane32_swap_b32_e32 v48, v49
	v_max_f32_e32 v49, v49, v49
	v_max_f32_e32 v48, v48, v48
	v_max_f32_e32 v48, v48, v49
	v_sub_f32_e32 v49, v48, v121
	v_cmp_lt_f32_e32 vcc, s50, v49
	s_cbranch_vccz .LBB0_523
	v_max_f32_e32 v48, v48, v48
	v_max_f32_e32 v49, v121, v121
	v_max_f32_e32 v49, v49, v48
	v_sub_f32_e32 v48, v121, v49
	v_exp_f32_e32 v48, v48
	v_mov_b32_e32 v121, v49
	v_pk_mul_f32 v[16:17], v[16:17], v[48:49] op_sel_hi:[1,0]
	v_pk_mul_f32 v[14:15], v[14:15], v[48:49] op_sel_hi:[1,0]
	v_pk_mul_f32 v[12:13], v[12:13], v[48:49] op_sel_hi:[1,0]
	v_pk_mul_f32 v[10:11], v[10:11], v[48:49] op_sel_hi:[1,0]
	v_pk_mul_f32 v[8:9], v[8:9], v[48:49] op_sel_hi:[1,0]
	v_pk_mul_f32 v[6:7], v[6:7], v[48:49] op_sel_hi:[1,0]
	v_pk_mul_f32 v[4:5], v[4:5], v[48:49] op_sel_hi:[1,0]
	v_pk_mul_f32 v[2:3], v[2:3], v[48:49] op_sel_hi:[1,0]
	v_pk_mul_f32 v[32:33], v[32:33], v[48:49] op_sel_hi:[1,0]
	v_pk_mul_f32 v[30:31], v[30:31], v[48:49] op_sel_hi:[1,0]
	v_pk_mul_f32 v[28:29], v[28:29], v[48:49] op_sel_hi:[1,0]
	v_pk_mul_f32 v[26:27], v[26:27], v[48:49] op_sel_hi:[1,0]
	v_pk_mul_f32 v[24:25], v[24:25], v[48:49] op_sel_hi:[1,0]
	v_pk_mul_f32 v[22:23], v[22:23], v[48:49] op_sel_hi:[1,0]
	v_pk_mul_f32 v[20:21], v[20:21], v[48:49] op_sel_hi:[1,0]
	v_pk_mul_f32 v[18:19], v[18:19], v[48:49] op_sel_hi:[1,0]
	v_mul_f32_e32 v106, v106, v48
.LBB0_523:
	v_sub_f32_e32 v0, v0, v121
	v_exp_f32_e32 v122, v0
	v_sub_f32_e32 v0, v35, v121
	v_exp_f32_e32 v123, v0
	v_sub_f32_e32 v0, v34, v121
	v_exp_f32_e32 v124, v0
	v_sub_f32_e32 v0, v37, v121
	v_exp_f32_e32 v125, v0
	v_sub_f32_e32 v0, v36, v121
	v_exp_f32_e32 v126, v0
	v_sub_f32_e32 v0, v39, v121
	v_sub_f32_e32 v48, v78, v121
	v_exp_f32_e32 v127, v0
	v_sub_f32_e32 v0, v38, v121
	v_exp_f32_e32 v107, v48
	v_exp_f32_e32 v128, v0
	v_sub_f32_e32 v0, v41, v121
	v_exp_f32_e32 v129, v0
	v_sub_f32_e32 v0, v40, v121
	v_exp_f32_e32 v130, v0
	v_sub_f32_e32 v0, v43, v121
	v_exp_f32_e32 v131, v0
	v_sub_f32_e32 v0, v42, v121
	v_exp_f32_e32 v132, v0
	v_sub_f32_e32 v0, v45, v121
	v_cvt_pk_bf16_f32 v34, v107, v122
	v_cvt_pk_bf16_f32 v35, v123, v124
	v_cvt_pk_bf16_f32 v36, v125, v126
	v_cvt_pk_bf16_f32 v37, v127, v128
	v_exp_f32_e32 v133, v0
	v_sub_f32_e32 v0, v44, v121
	s_waitcnt vmcnt(6)
	v_mfma_f32_32x32x16_bf16 v[2:17], v[66:69], v[34:37], v[2:17]
	v_exp_f32_e32 v134, v0
	v_sub_f32_e32 v0, v47, v121
	v_exp_f32_e32 v135, v0
	v_sub_f32_e32 v0, v46, v121
	v_exp_f32_e32 v136, v0
	s_add_i32 s64, s71, 0x80
	v_or_b32_e32 v0, s64, v109
	s_waitcnt vmcnt(4)
	v_mfma_f32_32x32x16_bf16 v[18:33], v[70:73], v[34:37], v[18:33]
	v_cvt_pk_bf16_f32 v34, v129, v130
	v_cvt_pk_bf16_f32 v35, v131, v132
	v_cvt_pk_bf16_f32 v36, v133, v134
	v_cvt_pk_bf16_f32 v37, v135, v136
	s_addk_i32 s71, 0x90
	s_waitcnt vmcnt(2)
	v_mfma_f32_32x32x16_bf16 v[2:17], v[74:77], v[34:37], v[2:17]
	s_waitcnt vmcnt(0)
	v_mfma_f32_32x32x16_bf16 v[18:33], v[82:85], v[34:37], v[18:33]
	v_mul_hi_u32 v34, v0, s51
	v_lshrrev_b32_e32 v34, 5, v34
	v_mul_i32_i24_e32 v35, 0xffffffd8, v34
	v_add_lshl_u32 v34, v34, v111, 6
	v_add_u32_e32 v0, v0, v112
	v_add3_u32 v34, v0, v35, v34
	v_ashrrev_i32_e32 v35, 31, v34
	v_lshlrev_b64 v[34:35], 9, v[34:35]
	v_lshl_add_u64 v[38:39], v[98:99], 0, v[34:35]
	global_load_dwordx4 v[34:37], v[38:39], off
	global_load_dwordx4 v[90:93], v[38:39], off offset:32
	global_load_dwordx4 v[86:89], v[38:39], off offset:64
	global_load_dwordx4 v[82:85], v[38:39], off offset:96
	v_or_b32_e32 v0, s64, v118
	s_add_i32 s64, s70, 0x666680
	v_mul_hi_u32 v38, v0, s51
	s_lshr_b32 s64, s64, 21
	v_lshrrev_b32_e32 v38, 5, v38
	v_add_lshl_u32 v39, v111, s64, 12
	v_add_lshl_u32 v40, v38, v111, 12
	v_mul_i32_i24_e32 v38, 0xffffffd8, v38
	v_add_u32_e32 v0, v0, v104
	v_add3_u32 v0, v0, v38, v40
	v_or_b32_e32 v38, v39, v113
	v_or_b32_e32 v42, v39, v115
	v_lshlrev_b32_e32 v38, 1, v38
	v_mov_b32_e32 v39, v1
	v_lshl_add_u64 v[38:39], v[100:101], 0, v[38:39]
	global_load_dwordx2 v[70:71], v[38:39], off offset:16
	v_lshlrev_b64 v[38:39], 1, v[0:1]
	v_lshl_add_u64 v[40:41], v[100:101], 0, v[38:39]
	v_lshlrev_b32_e32 v0, 1, v42
	v_lshl_add_u64 v[38:39], v[102:103], 0, v[38:39]
	global_load_dwordx2 v[72:73], v[40:41], off
	global_load_dwordx2 v[68:69], v[38:39], off
	v_lshl_add_u64 v[40:41], v[102:103], 0, v[0:1]
	v_or_b32_e32 v0, s71, v118
	s_add_i32 s70, s70, 0x733350
	v_mul_hi_u32 v38, v0, s51
	s_lshr_b32 s64, s70, 21
	v_lshrrev_b32_e32 v38, 5, v38
	global_load_dwordx2 v[66:67], v[40:41], off
	v_add_lshl_u32 v39, v111, s64, 12
	v_add_lshl_u32 v40, v38, v111, 12
	v_mul_i32_i24_e32 v38, 0xffffffd8, v38
	v_add_u32_e32 v0, v0, v104
	v_add3_u32 v0, v0, v38, v40
	v_or_b32_e32 v38, v39, v113
	v_or_b32_e32 v42, v39, v116
	v_lshlrev_b32_e32 v38, 1, v38
	v_mov_b32_e32 v39, v1
	v_lshl_add_u64 v[38:39], v[100:101], 0, v[38:39]
	global_load_dwordx2 v[78:79], v[38:39], off offset:48
	v_lshlrev_b64 v[38:39], 1, v[0:1]
	v_lshl_add_u64 v[40:41], v[100:101], 0, v[38:39]
	v_lshlrev_b32_e32 v0, 1, v42
	v_lshl_add_u64 v[38:39], v[102:103], 0, v[38:39]
	global_load_dwordx2 v[80:81], v[40:41], off
	global_load_dwordx2 v[76:77], v[38:39], off
	v_lshl_add_u64 v[40:41], v[102:103], 0, v[0:1]
	global_load_dwordx2 v[74:75], v[40:41], off
	s_waitcnt vmcnt(11)
	v_mfma_f32_32x32x16_bf16 v[34:49], v[34:37], v[50:53], 0
	v_mov_b32_e32 v0, 0xff800000
	s_waitcnt vmcnt(10)
	v_mfma_f32_32x32x16_bf16 v[34:49], v[90:93], v[54:57], v[34:49]
	s_waitcnt vmcnt(9)
	v_mfma_f32_32x32x16_bf16 v[34:49], v[86:89], v[58:61], v[34:49]
	s_waitcnt vmcnt(8)
	v_mfma_f32_32x32x16_bf16 v[34:49], v[82:85], v[62:65], v[34:49]
	v_mov_b32_e32 v218, 0xff800000
	ds_read_b32 v202, v120 offset:1332
	ds_read_b32 v203, v120 offset:1336
	ds_read_b32 v204, v120 offset:1340
	ds_read_b32 v205, v120 offset:1344
	ds_read_b32 v206, v120 offset:1364
	ds_read_b32 v207, v120 offset:1368
	ds_read_b32 v208, v120 offset:1372
	ds_read_b32 v209, v120 offset:1376
	ds_read_b32 v210, v120 offset:1396
	ds_read_b32 v211, v120 offset:1400
	ds_read_b32 v212, v120 offset:1404
	ds_read_b32 v213, v120 offset:1408
	ds_read_b32 v214, v120 offset:1428
	ds_read_b32 v215, v120 offset:1432
	ds_read_b32 v216, v120 offset:1436
	ds_read_b32 v217, v120 offset:1440
	s_waitcnt lgkmcnt(0)
	v_add_f32_e32 v202, v34, v202
	v_add_f32_e32 v203, v35, v203
	v_add_f32_e32 v204, v36, v204
	v_add_f32_e32 v205, v37, v205
	v_add_f32_e32 v206, v38, v206
	v_add_f32_e32 v207, v39, v207
	v_add_f32_e32 v208, v40, v208
	v_add_f32_e32 v209, v41, v209
	v_add_f32_e32 v210, v42, v210
	v_add_f32_e32 v211, v43, v211
	v_add_f32_e32 v212, v44, v212
	v_add_f32_e32 v213, v45, v213
	v_add_f32_e32 v214, v46, v214
	v_add_f32_e32 v215, v47, v215
	v_add_f32_e32 v216, v48, v216
	v_add_f32_e32 v217, v49, v217
	v_cndmask_b32_e64 v82, v218, v202, s[10:11]
	v_cndmask_b32_e64 v0, v218, v203, s[12:13]
	v_cndmask_b32_e64 v35, v218, v204, s[14:15]
	v_cndmask_b32_e64 v34, v218, v205, s[16:17]
	v_cndmask_b32_e64 v37, v218, v206, s[18:19]
	v_cndmask_b32_e64 v36, v218, v207, s[20:21]
	v_cndmask_b32_e64 v39, v218, v208, s[22:23]
	v_cndmask_b32_e64 v38, v218, v209, s[24:25]
	v_cndmask_b32_e64 v83, v218, v210, s[26:27]
	v_cndmask_b32_e64 v41, v218, v211, s[28:29]
	v_cndmask_b32_e64 v84, v218, v212, s[30:31]
	v_cndmask_b32_e64 v40, v218, v213, s[34:35]
	v_cndmask_b32_e64 v43, v218, v214, s[36:37]
	v_cndmask_b32_e64 v42, v218, v215, s[38:39]
	v_cndmask_b32_e64 v46, v218, v216, s[40:41]
	v_cndmask_b32_e64 v45, v218, v217, s[42:43]
	s_mov_b32 s64, 0xff800000
	v_max3_f32 v44, v82, s64, v0
	v_max3_f32 v44, v44, v35, v34
	v_max3_f32 v44, v44, v37, v36
	v_max3_f32 v44, v44, v39, v38
	v_max3_f32 v44, v44, v83, v41
	v_max3_f32 v44, v44, v84, v40
	v_max3_f32 v47, v44, v43, v42
	v_add_f32_e32 v44, 0, v107
	v_add_f32_e32 v44, v122, v44
	v_add_f32_e32 v44, v123, v44
	v_add_f32_e32 v44, v124, v44
	v_add_f32_e32 v44, v125, v44
	v_add_f32_e32 v44, v126, v44
	v_add_f32_e32 v44, v127, v44
	v_add_f32_e32 v44, v128, v44
	v_add_f32_e32 v44, v129, v44
	v_add_f32_e32 v44, v130, v44
	v_add_f32_e32 v44, v131, v44
	v_max3_f32 v47, v47, v46, v45
	v_add_f32_e32 v44, v132, v44
	v_mov_b32_e32 v48, v47
	v_add_f32_e32 v44, v133, v44
	s_nop 0
	v_permlane32_swap_b32_e32 v47, v48
	v_add_f32_e32 v44, v134, v44
	v_max_f32_e32 v48, v48, v48
	v_max_f32_e32 v47, v47, v47
	v_add_f32_e32 v44, v135, v44
	v_max_f32_e32 v47, v47, v48
	v_add_f32_e32 v44, v136, v44
	v_sub_f32_e32 v48, v47, v121
	v_add_f32_e32 v44, v106, v44
	v_cmp_lt_f32_e32 vcc, s50, v48
	s_cbranch_vccz .LBB0_386
	v_max_f32_e32 v47, v47, v47
	v_max_f32_e32 v48, v121, v121
	v_max_f32_e32 v47, v48, v47
	v_sub_f32_e32 v48, v121, v47
	v_exp_f32_e32 v48, v48
	v_mov_b32_e32 v121, v47
	v_pk_mul_f32 v[16:17], v[16:17], v[48:49] op_sel_hi:[1,0]
	v_pk_mul_f32 v[14:15], v[14:15], v[48:49] op_sel_hi:[1,0]
	v_pk_mul_f32 v[12:13], v[12:13], v[48:49] op_sel_hi:[1,0]
	v_pk_mul_f32 v[10:11], v[10:11], v[48:49] op_sel_hi:[1,0]
	v_pk_mul_f32 v[8:9], v[8:9], v[48:49] op_sel_hi:[1,0]
	v_pk_mul_f32 v[6:7], v[6:7], v[48:49] op_sel_hi:[1,0]
	v_pk_mul_f32 v[4:5], v[4:5], v[48:49] op_sel_hi:[1,0]
	v_pk_mul_f32 v[2:3], v[2:3], v[48:49] op_sel_hi:[1,0]
	v_pk_mul_f32 v[32:33], v[32:33], v[48:49] op_sel_hi:[1,0]
	v_pk_mul_f32 v[30:31], v[30:31], v[48:49] op_sel_hi:[1,0]
	v_pk_mul_f32 v[28:29], v[28:29], v[48:49] op_sel_hi:[1,0]
	v_pk_mul_f32 v[26:27], v[26:27], v[48:49] op_sel_hi:[1,0]
	v_pk_mul_f32 v[24:25], v[24:25], v[48:49] op_sel_hi:[1,0]
	v_pk_mul_f32 v[22:23], v[22:23], v[48:49] op_sel_hi:[1,0]
	v_pk_mul_f32 v[20:21], v[20:21], v[48:49] op_sel_hi:[1,0]
	v_pk_mul_f32 v[18:19], v[18:19], v[48:49] op_sel_hi:[1,0]
	v_mul_f32_e32 v44, v44, v48
	s_branch .LBB0_386
